# v20 plus: attention queue pop uses the returning atomic add alone (pre-load round trip removed)
# baseline (speedup 1.0000x reference)
; #define LAS __attribute__((address_space(3)))
; __device__ __forceinline__ int otid() { int t = threadIdx.x; asm volatile("" : "+v"(t)); return t; }
; __global__ void __launch_bounds__(512, 2) fwd_megakernel(Params p0) {
;     ...
;                         if (otid() == 0) { int v = __hip_atomic_load(ctr + bq, __ATOMIC_RELAXED, __HIP_MEMORY_SCOPE_AGENT); if (v < 64) v = atomicAdd(ctr + bq, 1); *(LAS int*)(lds + LDS_CTL) = v; }
.LBB0_170:
	v_mov_b32_e32 v0, v190
	s_barrier
	s_nop 0
	v_cmp_eq_u32_e32 vcc, 0, v0
	s_and_saveexec_b64 s[20:21], vcc
	s_cbranch_execz .LBB0_176
	s_mov_b64 s[28:29], exec
	v_mbcnt_lo_u32_b32 v0, s28, 0
	v_mbcnt_hi_u32_b32 v0, s29, v0
	v_cmp_eq_u32_e32 vcc, 0, v0
	s_and_saveexec_b64 s[22:23], vcc
	s_cbranch_execz .LBB0_174
	s_bcnt1_i32_b64 s28, s[28:29]
	v_mov_b32_e32 v1, s28
	global_atomic_add v1, v96, v1, s[18:19] sc0
